# FFN-norm phase: the four split-K slabs and the gate vector of each context-row piece are requested together (5 serial round trips per piece before), same summation order; otherwise as v82
# speedup vs baseline: 1.0048x; 1.0000x over previous
; __device__ __forceinline__ void norm_load(NormRow& R, const NormPar& P, int lane) {
;     const f32x4* xr = (const f32x4*)P.src + lane; R.s = 0.f;
; #pragma unroll
;     for (int j = 0; j < 4; ++j) { R.v[j] = xr[64 * j];
;         if (P.part) { f32x4 a = (f32x4){0.f, 0.f, 0.f, 0.f};
;             for (int q = 0; q < P.nsl; ++q) a = a + ((const f32x4*)(P.part + (size_t)q * 512 * 1024))[64 * j + lane];
;             R.v[j] = R.v[j] + ((const f32x4*)P.gv)[64 * j + lane] * a; }
;         R.s += (R.v[j][0] * R.v[j][0] + R.v[j][1] * R.v[j][1]) + (R.v[j][2] * R.v[j][2] + R.v[j][3] * R.v[j][3]); }
; }
; __global__ void __launch_bounds__(NTHR, 2) mk_fwd(Args args) {
;     ...
;                 for (int t = gw; t < MT; t += 2 * NGW) {
;                     const int tB = t + NGW; const bool hb = tB < MT;
;                     const int tBc = hb ? tB : t;
;                     NormPar PA, PB; NormRow RA, RB; NORM2_PAR(PA, t); NORM2_PAR(PB, tBc);
;                     norm_load(RA, PA, lane); norm_load(RB, PB, lane);
.LBB0_133:
	v_lshl_add_u64 v[62:63], s[4:5], 0, v[56:57]
	v_add_co_u32_e32 v0, vcc, 0x4c0000, v62
	s_cmpk_gt_i32 s11, 0x20ff
	s_nop 0
	v_addc_co_u32_e32 v1, vcc, 0, v63, vcc
	global_load_dwordx4 v[24:27], v[0:1], off
	s_cselect_b64 s[36:37], -1, 0
	s_and_b64 s[0:1], s[36:37], exec
	s_cselect_b32 s0, 0xffffdf00, 0
	s_cselect_b32 s1, 0x100, 0
	s_add_i32 s0, s0, s11
	s_cmpk_gt_i32 s0, 0xff
	s_cselect_b64 s[44:45], -1, 0
	s_add_i32 s0, s0, s1
	s_ashr_i32 s1, s0, 31
	s_lshl_b64 s[0:1], s[0:1], 12
	s_add_u32 s0, s13, s0
	s_addc_u32 s1, s26, s1
	s_or_b64 s[18:19], s[44:45], s[2:3]
	s_and_b64 vcc, exec, s[18:19]
	v_lshlrev_b32_e32 v58, 4, v202
	s_cbranch_vccnz .LBB0_135
	global_load_dwordx4 v[140:143], v58, s[0:1]
	v_mov_b32_e32 v59, v36
	v_add_u32_e32 v156, 0x200000, v58
	global_load_dwordx4 v[144:147], v156, s[0:1]
	v_add_u32_e32 v157, 0x400000, v58
	global_load_dwordx4 v[148:151], v157, s[0:1]
	v_add_u32_e32 v158, 0x600000, v58
	global_load_dwordx4 v[152:155], v158, s[0:1]
	global_load_dwordx4 v[0:3], v[32:33], off
	s_waitcnt vmcnt(4)
	v_pk_add_f32 v[8:9], v[140:141], 0 op_sel_hi:[1,0]
	v_pk_add_f32 v[6:7], v[142:143], 0 op_sel_hi:[1,0]
	s_waitcnt vmcnt(3)
	v_pk_add_f32 v[8:9], v[8:9], v[144:145]
	v_pk_add_f32 v[6:7], v[6:7], v[146:147]
	s_waitcnt vmcnt(2)
	v_pk_add_f32 v[8:9], v[8:9], v[148:149]
	v_pk_add_f32 v[6:7], v[6:7], v[150:151]
	s_waitcnt vmcnt(1)
	v_pk_add_f32 v[4:5], v[6:7], v[154:155]
	v_pk_add_f32 v[6:7], v[8:9], v[152:153]
	s_waitcnt vmcnt(0)
	v_pk_fma_f32 v[26:27], v[4:5], v[2:3], v[26:27]
	v_pk_fma_f32 v[24:25], v[6:7], v[0:1], v[24:25]
.LBB0_135:
	v_add_co_u32_e32 v0, vcc, 0x4c0000, v62
	s_xor_b64 s[18:19], s[18:19], -1
	s_nop 0
	v_addc_co_u32_e32 v1, vcc, 0, v63, vcc
	global_load_dwordx4 v[16:19], v[0:1], off offset:1024
	v_cndmask_b32_e64 v0, 0, 1, s[18:19]
	v_cmp_ne_u32_e64 s[40:41], 1, v0
	s_andn2_b64 vcc, exec, s[18:19]
	s_cbranch_vccnz .LBB0_137
	global_load_dwordx4 v[140:143], v58, s[0:1] offset:1024
	v_mov_b32_e32 v59, v36
	v_add_u32_e32 v156, 0x200000, v58
	global_load_dwordx4 v[144:147], v156, s[0:1] offset:1024
	v_add_u32_e32 v157, 0x400000, v58
	global_load_dwordx4 v[148:151], v157, s[0:1] offset:1024
	v_add_u32_e32 v158, 0x600000, v58
	global_load_dwordx4 v[152:155], v158, s[0:1] offset:1024
	global_load_dwordx4 v[0:3], v[34:35], off
	s_waitcnt vmcnt(4)
	v_pk_add_f32 v[8:9], v[140:141], 0 op_sel_hi:[1,0]
	v_pk_add_f32 v[6:7], v[142:143], 0 op_sel_hi:[1,0]
	s_waitcnt vmcnt(3)
	v_pk_add_f32 v[8:9], v[8:9], v[144:145]
	v_pk_add_f32 v[6:7], v[6:7], v[146:147]
	s_waitcnt vmcnt(2)
	v_pk_add_f32 v[8:9], v[8:9], v[148:149]
	v_pk_add_f32 v[6:7], v[6:7], v[150:151]
	s_waitcnt vmcnt(1)
	v_pk_add_f32 v[4:5], v[6:7], v[154:155]
	v_pk_add_f32 v[6:7], v[8:9], v[152:153]
	s_waitcnt vmcnt(0)
	v_pk_fma_f32 v[18:19], v[4:5], v[2:3], v[18:19]
	v_pk_fma_f32 v[16:17], v[6:7], v[0:1], v[16:17]
.LBB0_137:
	v_add_co_u32_e32 v0, vcc, 0x4c0000, v62
	s_nop 1
	v_addc_co_u32_e32 v1, vcc, 0, v63, vcc
	global_load_dwordx4 v[20:23], v[0:1], off offset:2048
	s_and_b64 vcc, exec, s[40:41]
	s_cbranch_vccnz .LBB0_139
	global_load_dwordx4 v[140:143], v58, s[0:1] offset:2048
	v_mov_b32_e32 v59, v36
	v_add_u32_e32 v156, 0x200000, v58
	global_load_dwordx4 v[144:147], v156, s[0:1] offset:2048
	v_add_u32_e32 v157, 0x400000, v58
	global_load_dwordx4 v[148:151], v157, s[0:1] offset:2048
	v_add_u32_e32 v158, 0x600000, v58
	global_load_dwordx4 v[152:155], v158, s[0:1] offset:2048
	global_load_dwordx4 v[0:3], v[38:39], off
	s_waitcnt vmcnt(4)
	v_pk_add_f32 v[8:9], v[140:141], 0 op_sel_hi:[1,0]
	v_pk_add_f32 v[6:7], v[142:143], 0 op_sel_hi:[1,0]
	s_waitcnt vmcnt(3)
	v_pk_add_f32 v[8:9], v[8:9], v[144:145]
	v_pk_add_f32 v[6:7], v[6:7], v[146:147]
	s_waitcnt vmcnt(2)
	v_pk_add_f32 v[8:9], v[8:9], v[148:149]
	v_pk_add_f32 v[6:7], v[6:7], v[150:151]
	s_waitcnt vmcnt(1)
	v_pk_add_f32 v[4:5], v[6:7], v[154:155]
	v_pk_add_f32 v[6:7], v[8:9], v[152:153]
	s_waitcnt vmcnt(0)
	v_pk_fma_f32 v[22:23], v[4:5], v[2:3], v[22:23]
	v_pk_fma_f32 v[20:21], v[6:7], v[0:1], v[20:21]
.LBB0_139:
	v_add_co_u32_e32 v0, vcc, 0x4c0000, v62
	s_nop 1
	v_addc_co_u32_e32 v1, vcc, 0, v63, vcc
	global_load_dwordx4 v[28:31], v[0:1], off offset:3072
	s_and_b64 vcc, exec, s[40:41]
	s_cbranch_vccnz .LBB0_141
	global_load_dwordx4 v[140:143], v58, s[0:1] offset:3072
	v_mov_b32_e32 v59, v36
	v_add_u32_e32 v156, 0x200000, v58
	global_load_dwordx4 v[144:147], v156, s[0:1] offset:3072
	v_add_u32_e32 v157, 0x400000, v58
	global_load_dwordx4 v[148:151], v157, s[0:1] offset:3072
	v_add_u32_e32 v158, 0x600000, v58
	global_load_dwordx4 v[152:155], v158, s[0:1] offset:3072
	global_load_dwordx4 v[0:3], v[42:43], off
	s_waitcnt vmcnt(4)
	v_pk_add_f32 v[8:9], v[140:141], 0 op_sel_hi:[1,0]
	v_pk_add_f32 v[6:7], v[142:143], 0 op_sel_hi:[1,0]
	s_waitcnt vmcnt(3)
	v_pk_add_f32 v[8:9], v[8:9], v[144:145]
	v_pk_add_f32 v[6:7], v[6:7], v[146:147]
	s_waitcnt vmcnt(2)
	v_pk_add_f32 v[8:9], v[8:9], v[148:149]
	v_pk_add_f32 v[6:7], v[6:7], v[150:151]
	s_waitcnt vmcnt(1)
	v_pk_add_f32 v[4:5], v[6:7], v[154:155]
	v_pk_add_f32 v[6:7], v[8:9], v[152:153]
	s_waitcnt vmcnt(0)
	v_pk_fma_f32 v[30:31], v[4:5], v[2:3], v[30:31]
	v_pk_fma_f32 v[28:29], v[6:7], v[0:1], v[28:29]
.LBB0_141:
	v_readlane_b32 s0, v254, 23
	s_add_i32 s18, s0, s11
	s_cmpk_lt_i32 s18, 0x4200
	v_readlane_b32 s1, v254, 24
	s_cselect_b64 s[42:43], -1, 0
	s_and_b64 s[0:1], s[42:43], exec
	s_cselect_b32 s34, s18, s11
	s_cmpk_gt_i32 s34, 0x20ff
	s_cselect_b64 s[28:29], -1, 0
	s_and_b64 s[0:1], s[28:29], exec
	s_cselect_b32 s0, 0xffffdf00, 0
	s_cselect_b32 s1, 0x100, 0
	s_add_i32 s0, s0, s34
	s_cmpk_gt_i32 s0, 0xff
	s_cselect_b64 s[30:31], -1, 0
	s_add_i32 s0, s0, s1
	s_ashr_i32 s1, s0, 31
	s_ashr_i32 s35, s34, 31
	s_lshl_b64 s[0:1], s[0:1], 12
	s_add_u32 s0, s13, s0
	s_addc_u32 s1, s26, s1
	s_lshl_b64 s[18:19], s[34:35], 12
	v_lshl_add_u64 v[60:61], v[50:51], 0, s[18:19]
	global_load_dwordx4 v[8:11], v[60:61], off
	s_or_b64 s[18:19], s[30:31], s[2:3]
	s_and_b64 vcc, exec, s[18:19]
	s_cbranch_vccnz .LBB0_143
	global_load_dwordx4 v[140:143], v58, s[0:1]
	v_mov_b32_e32 v59, v36
	v_add_u32_e32 v156, 0x200000, v58
	global_load_dwordx4 v[144:147], v156, s[0:1]
	v_add_u32_e32 v157, 0x400000, v58
	global_load_dwordx4 v[148:151], v157, s[0:1]
	v_add_u32_e32 v158, 0x600000, v58
	global_load_dwordx4 v[152:155], v158, s[0:1]
	global_load_dwordx4 v[0:3], v[32:33], off
	s_waitcnt vmcnt(4)
	v_pk_add_f32 v[12:13], v[140:141], 0 op_sel_hi:[1,0]
	v_pk_add_f32 v[6:7], v[142:143], 0 op_sel_hi:[1,0]
	s_waitcnt vmcnt(3)
	v_pk_add_f32 v[12:13], v[12:13], v[144:145]
	v_pk_add_f32 v[6:7], v[6:7], v[146:147]
	s_waitcnt vmcnt(2)
	v_pk_add_f32 v[12:13], v[12:13], v[148:149]
	v_pk_add_f32 v[6:7], v[6:7], v[150:151]
	s_waitcnt vmcnt(1)
	v_pk_add_f32 v[4:5], v[6:7], v[154:155]
	v_pk_add_f32 v[6:7], v[12:13], v[152:153]
	s_waitcnt vmcnt(0)
	v_pk_fma_f32 v[10:11], v[4:5], v[2:3], v[10:11]
	v_pk_fma_f32 v[8:9], v[6:7], v[0:1], v[8:9]

; __device__ __forceinline__ void norm_load(NormRow& R, const NormPar& P, int lane) {
;     const f32x4* xr = (const f32x4*)P.src + lane; R.s = 0.f;
; #pragma unroll
;     for (int j = 0; j < 4; ++j) { R.v[j] = xr[64 * j];
;         if (P.part) { f32x4 a = (f32x4){0.f, 0.f, 0.f, 0.f};
;             for (int q = 0; q < P.nsl; ++q) a = a + ((const f32x4*)(P.part + (size_t)q * 512 * 1024))[64 * j + lane];
;             R.v[j] = R.v[j] + ((const f32x4*)P.gv)[64 * j + lane] * a; }
;         R.s += (R.v[j][0] * R.v[j][0] + R.v[j][1] * R.v[j][1]) + (R.v[j][2] * R.v[j][2] + R.v[j][3] * R.v[j][3]); }
; }
; __global__ void __launch_bounds__(NTHR, 2) mk_fwd(Args args) {
;     ...
;                 for (int t = gw; t < MT; t += 2 * NGW) {
;                     const int tB = t + NGW; const bool hb = tB < MT;
;                     const int tBc = hb ? tB : t;
;                     NormPar PA, PB; NormRow RA, RB; NORM2_PAR(PA, t); NORM2_PAR(PB, tBc);
;                     norm_load(RA, PA, lane); norm_load(RB, PB, lane);
.LBB0_151:
	global_load_dwordx4 v[140:143], v58, s[0:1] offset:1024
	v_mov_b32_e32 v59, v36
	v_add_u32_e32 v156, 0x200000, v58
	global_load_dwordx4 v[144:147], v156, s[0:1] offset:1024
	v_add_u32_e32 v157, 0x400000, v58
	global_load_dwordx4 v[148:151], v157, s[0:1] offset:1024
	v_add_u32_e32 v158, 0x600000, v58
	global_load_dwordx4 v[152:155], v158, s[0:1] offset:1024
	global_load_dwordx4 v[4:7], v[34:35], off
	s_waitcnt vmcnt(4)
	v_pk_add_f32 v[72:73], v[140:141], 0 op_sel_hi:[1,0]
	v_pk_add_f32 v[14:15], v[142:143], 0 op_sel_hi:[1,0]
	s_waitcnt vmcnt(3)
	v_pk_add_f32 v[72:73], v[72:73], v[144:145]
	v_pk_add_f32 v[14:15], v[14:15], v[146:147]
	s_waitcnt vmcnt(2)
	v_pk_add_f32 v[72:73], v[72:73], v[148:149]
	v_pk_add_f32 v[14:15], v[14:15], v[150:151]
	s_waitcnt vmcnt(1)
	v_pk_add_f32 v[12:13], v[14:15], v[154:155]
	v_pk_add_f32 v[14:15], v[72:73], v[152:153]
	s_waitcnt vmcnt(0)
	v_pk_fma_f32 v[2:3], v[12:13], v[6:7], v[2:3]
	v_pk_fma_f32 v[0:1], v[14:15], v[4:5], v[0:1]
	global_load_dwordx4 v[4:7], v[60:61], off offset:2048
	s_and_b64 vcc, exec, s[38:39]
	s_cbranch_vccnz .LBB0_145
.LBB0_152:
	global_load_dwordx4 v[140:143], v58, s[0:1] offset:2048
	v_mov_b32_e32 v59, v36
	v_add_u32_e32 v156, 0x200000, v58
	global_load_dwordx4 v[144:147], v156, s[0:1] offset:2048
	v_add_u32_e32 v157, 0x400000, v58
	global_load_dwordx4 v[148:151], v157, s[0:1] offset:2048
	v_add_u32_e32 v158, 0x600000, v58
	global_load_dwordx4 v[152:155], v158, s[0:1] offset:2048
	global_load_dwordx4 v[12:15], v[38:39], off
	s_waitcnt vmcnt(4)
	v_pk_add_f32 v[76:77], v[140:141], 0 op_sel_hi:[1,0]
	v_pk_add_f32 v[74:75], v[142:143], 0 op_sel_hi:[1,0]
	s_waitcnt vmcnt(3)
	v_pk_add_f32 v[76:77], v[76:77], v[144:145]
	v_pk_add_f32 v[74:75], v[74:75], v[146:147]
	s_waitcnt vmcnt(2)
	v_pk_add_f32 v[76:77], v[76:77], v[148:149]
	v_pk_add_f32 v[74:75], v[74:75], v[150:151]
	s_waitcnt vmcnt(1)
	v_pk_add_f32 v[72:73], v[74:75], v[154:155]
	v_pk_add_f32 v[74:75], v[76:77], v[152:153]
	s_waitcnt vmcnt(0)
	v_pk_fma_f32 v[6:7], v[72:73], v[14:15], v[6:7]
	v_pk_fma_f32 v[4:5], v[74:75], v[12:13], v[4:5]
	global_load_dwordx4 v[12:15], v[60:61], off offset:3072
	s_and_b64 vcc, exec, s[38:39]
	s_cbranch_vccnz .LBB0_146
.LBB0_153:
	global_load_dwordx4 v[140:143], v58, s[0:1] offset:3072
	v_mov_b32_e32 v59, v36
	v_add_u32_e32 v156, 0x200000, v58
	global_load_dwordx4 v[144:147], v156, s[0:1] offset:3072
	v_add_u32_e32 v157, 0x400000, v58
	global_load_dwordx4 v[148:151], v157, s[0:1] offset:3072
	v_add_u32_e32 v158, 0x600000, v58
	global_load_dwordx4 v[152:155], v158, s[0:1] offset:3072
	global_load_dwordx4 v[72:75], v[42:43], off
	s_waitcnt vmcnt(4)
	v_pk_add_f32 v[80:81], v[140:141], 0 op_sel_hi:[1,0]
	v_pk_add_f32 v[78:79], v[142:143], 0 op_sel_hi:[1,0]
	s_waitcnt vmcnt(3)
	v_pk_add_f32 v[80:81], v[80:81], v[144:145]
	v_pk_add_f32 v[78:79], v[78:79], v[146:147]
	s_waitcnt vmcnt(2)
	v_pk_add_f32 v[80:81], v[80:81], v[148:149]
	v_pk_add_f32 v[78:79], v[78:79], v[150:151]
	s_waitcnt vmcnt(1)
	v_pk_add_f32 v[76:77], v[78:79], v[154:155]
	v_pk_add_f32 v[78:79], v[80:81], v[152:153]
	s_waitcnt vmcnt(0)
	v_pk_fma_f32 v[14:15], v[76:77], v[74:75], v[14:15]
	v_pk_fma_f32 v[12:13], v[78:79], v[72:73], v[12:13]
	s_and_b64 vcc, exec, s[40:41]
	s_cbranch_vccz .LBB0_147
	s_branch .LBB0_148
